# v30 + gate/up GEMM with the two wave groups left skewed by one phase through the epilogue (the template's ALIGN_EPI=false form: two per-tile conditional barriers dropped, one re-align at phase end)
# baseline (speedup 1.0000x reference)
.Lgu_kdone:
.LBB0_149:
	s_bitcmp1_b32 s47, 0
	s_cselect_b64 s[24:25], -1, 0
	s_and_b64 vcc, exec, s[24:25]
	s_cbranch_vccnz .LBB0_151
	s_and_b64 s[24:25], s[12:13], exec
	s_cselect_b32 s15, s22, s49
	v_lshl_or_b32 v140, s15, 8, v145
	v_ashrrev_i32_e32 v141, 31, v140
	v_lshlrev_b64 v[140:141], 6, v[140:141]
	v_lshl_add_u64 v[140:141], s[4:5], 0, v[140:141]
	global_load_dwordx4 v[150:153], v[140:141], off offset:48
	global_load_dwordx4 v[154:157], v[140:141], off offset:32
	global_load_dwordx4 v[158:161], v[140:141], off offset:16
	global_load_dwordx4 v[162:165], v[140:141], off
	s_waitcnt vmcnt(0)
	v_add_f32_e32 v154, v154, v155
	v_add_f32_e32 v156, v156, v157
	v_mov_b32_e32 v140, v163
	v_mov_b32_e32 v141, v164
	v_mov_b32_e32 v163, v165
	v_pk_add_f32 v[140:141], v[140:141], v[162:163]
	v_mov_b32_e32 v162, v159
	v_mov_b32_e32 v163, v160
	v_mov_b32_e32 v159, v161
	v_pk_add_f32 v[158:159], v[162:163], v[158:159]
	v_pk_add_f32 v[140:141], v[140:141], v[140:141] op_sel:[0,1] op_sel_hi:[1,0]
	v_pk_add_f32 v[158:159], v[158:159], v[158:159] op_sel:[0,1] op_sel_hi:[1,0]
	v_mov_b32_e32 v141, v150
	v_mov_b32_e32 v159, v151
	v_mov_b32_e32 v155, v152
	v_mov_b32_e32 v157, v153
	v_pk_add_f32 v[140:141], v[140:141], v[158:159]
	v_pk_add_f32 v[150:151], v[154:155], v[156:157]
	s_nop 0
	v_pk_add_f32 v[140:141], v[140:141], v[150:151]
	s_nop 0
	v_add_f32_e32 v140, v140, v141
	v_fmamk_f32 v140, v140, 0x3a800000, v249
	v_rsq_f32_e32 v140, v140
	ds_write_b32 v147, v140
	s_waitcnt lgkmcnt(0)
	s_barrier
.LBB0_151:
	s_and_b32 s15, s47, 1
	v_lshl_add_u32 v150, s15, 10, v146
	ds_read_b32 v152, v150
	ds_read_b32 v153, v150 offset:64
	ds_read_b32 v154, v150 offset:128
	ds_read_b32 v155, v150 offset:192
	ds_read_b32 v156, v150 offset:512
	ds_read_b32 v157, v150 offset:576
	ds_read_b32 v158, v150 offset:640
	ds_read_b32 v159, v150 offset:704
	v_lshl_or_b32 v140, s23, 7, v144
	v_lshl_add_u32 v149, s22, 8, v142
	v_ashrrev_i32_e32 v141, 31, v140
	s_andn2_b64 vcc, exec, s[2:3]
	v_mov_b64_e32 v[162:163], s[8:9]
	v_lshlrev_b64 v[164:165], 1, v[140:141]
	v_mad_i64_i32 v[160:161], s[22:23], v149, s89, v[162:163]
	s_mov_b32 s100, 0x16000
	s_mov_b32 s101, 0
	s_mov_b32 s98, 0x6e000
	s_mov_b32 s99, 0
	v_lshl_add_u64 v[160:161], v[160:161], 0, v[164:165]
	s_waitcnt lgkmcnt(0)

	v_mul_f32_e32 v122, v122, v152
	v_mul_f32_e32 v126, v126, v152
	v_mul_f32_e32 v123, v123, v152
	v_mul_f32_e32 v127, v127, v152
	v_mul_f32_e32 v124, v124, v152
	v_mul_f32_e32 v128, v128, v152
	v_mul_f32_e32 v125, v125, v152
	v_mul_f32_e32 v129, v129, v152
	v_mul_f32_e32 v114, v114, v152
	v_mul_f32_e32 v118, v118, v152
	v_mul_f32_e32 v115, v115, v152
	v_mul_f32_e32 v119, v119, v152
	v_mul_f32_e32 v116, v116, v152
	v_mul_f32_e32 v120, v120, v152
	v_mul_f32_e32 v117, v117, v152
	v_mul_f32_e32 v121, v121, v152
	v_mul_f32_e32 v166, 0xbfb8aa3b, v126
	v_mul_f32_e32 v167, 0xbfb8aa3b, v127
	v_mul_f32_e32 v168, 0xbfb8aa3b, v128
	v_mul_f32_e32 v169, 0xbfb8aa3b, v129
	v_mul_f32_e32 v170, 0xbfb8aa3b, v118
	v_mul_f32_e32 v171, 0xbfb8aa3b, v119
	v_mul_f32_e32 v172, 0xbfb8aa3b, v120
	v_mul_f32_e32 v173, 0xbfb8aa3b, v121
	v_exp_f32_e32 v166, v166
	v_exp_f32_e32 v167, v167
	v_exp_f32_e32 v168, v168
	v_exp_f32_e32 v169, v169
	v_exp_f32_e32 v170, v170
	v_exp_f32_e32 v171, v171
	v_exp_f32_e32 v172, v172
	v_exp_f32_e32 v173, v173
	v_add_f32_e32 v166, 1.0, v166
	v_add_f32_e32 v167, 1.0, v167
	v_add_f32_e32 v168, 1.0, v168
	v_add_f32_e32 v169, 1.0, v169
	v_add_f32_e32 v170, 1.0, v170
	v_add_f32_e32 v171, 1.0, v171
	v_add_f32_e32 v172, 1.0, v172
	v_add_f32_e32 v173, 1.0, v173
	v_rcp_f32_e32 v166, v166
	v_rcp_f32_e32 v167, v167
	v_rcp_f32_e32 v168, v168
	v_rcp_f32_e32 v169, v169
	v_rcp_f32_e32 v170, v170
	v_rcp_f32_e32 v171, v171
	v_rcp_f32_e32 v172, v172
	v_rcp_f32_e32 v173, v173
	v_mul_f32_e32 v126, v126, v166
	v_mul_f32_e32 v127, v127, v167
	v_mul_f32_e32 v128, v128, v168
	v_mul_f32_e32 v129, v129, v169
	v_mul_f32_e32 v118, v118, v170
	v_mul_f32_e32 v119, v119, v171
	v_mul_f32_e32 v120, v120, v172
	v_mul_f32_e32 v121, v121, v173
	v_mul_f32_e32 v122, v122, v126
	v_mul_f32_e32 v123, v123, v127
	v_mul_f32_e32 v124, v124, v128
	v_mul_f32_e32 v125, v125, v129
	v_mul_f32_e32 v114, v114, v118
	v_mul_f32_e32 v115, v115, v119
	v_mul_f32_e32 v116, v116, v120
	v_mul_f32_e32 v117, v117, v121
	v_cvt_pk_bf16_f32 v126, v122, v123
	v_cvt_pk_bf16_f32 v127, v124, v125
	v_cvt_pk_bf16_f32 v128, v114, v115
	v_cvt_pk_bf16_f32 v129, v116, v117
	s_nop 0
	s_waitcnt vmcnt(0)
	global_store_dwordx4 v[160:161], v[126:129], off sc1
	v_lshl_add_u64 v[160:161], s[100:101], 0, v[160:161]
	v_mul_f32_e32 v106, v106, v153
	v_mul_f32_e32 v110, v110, v153
	v_mul_f32_e32 v107, v107, v153
	v_mul_f32_e32 v111, v111, v153
	v_mul_f32_e32 v108, v108, v153
	v_mul_f32_e32 v112, v112, v153
	v_mul_f32_e32 v109, v109, v153
	v_mul_f32_e32 v113, v113, v153
	v_mul_f32_e32 v98, v98, v153
	v_mul_f32_e32 v102, v102, v153
	v_mul_f32_e32 v99, v99, v153
	v_mul_f32_e32 v103, v103, v153
	v_mul_f32_e32 v100, v100, v153
	v_mul_f32_e32 v104, v104, v153
	v_mul_f32_e32 v101, v101, v153
	v_mul_f32_e32 v105, v105, v153
	v_mul_f32_e32 v166, 0xbfb8aa3b, v110
	v_mul_f32_e32 v167, 0xbfb8aa3b, v111
	v_mul_f32_e32 v168, 0xbfb8aa3b, v112
	v_mul_f32_e32 v169, 0xbfb8aa3b, v113
	v_mul_f32_e32 v170, 0xbfb8aa3b, v102
	v_mul_f32_e32 v171, 0xbfb8aa3b, v103
	v_mul_f32_e32 v172, 0xbfb8aa3b, v104
	v_mul_f32_e32 v173, 0xbfb8aa3b, v105
	v_exp_f32_e32 v166, v166
	v_exp_f32_e32 v167, v167
	v_exp_f32_e32 v168, v168
	v_exp_f32_e32 v169, v169
	v_exp_f32_e32 v170, v170
	v_exp_f32_e32 v171, v171
	v_exp_f32_e32 v172, v172
	v_exp_f32_e32 v173, v173
	v_add_f32_e32 v166, 1.0, v166
	v_add_f32_e32 v167, 1.0, v167
	v_add_f32_e32 v168, 1.0, v168
	v_add_f32_e32 v169, 1.0, v169
	v_add_f32_e32 v170, 1.0, v170
	v_add_f32_e32 v171, 1.0, v171
	v_add_f32_e32 v172, 1.0, v172
	v_add_f32_e32 v173, 1.0, v173
	v_rcp_f32_e32 v166, v166
	v_rcp_f32_e32 v167, v167
	v_rcp_f32_e32 v168, v168
	v_rcp_f32_e32 v169, v169
	v_rcp_f32_e32 v170, v170
	v_rcp_f32_e32 v171, v171
	v_rcp_f32_e32 v172, v172
	v_rcp_f32_e32 v173, v173
	v_mul_f32_e32 v110, v110, v166
	v_mul_f32_e32 v111, v111, v167
	v_mul_f32_e32 v112, v112, v168
	v_mul_f32_e32 v113, v113, v169
	v_mul_f32_e32 v102, v102, v170
	v_mul_f32_e32 v103, v103, v171
	v_mul_f32_e32 v104, v104, v172
	v_mul_f32_e32 v105, v105, v173
	v_mul_f32_e32 v106, v106, v110
	v_mul_f32_e32 v107, v107, v111
	v_mul_f32_e32 v108, v108, v112
	v_mul_f32_e32 v109, v109, v113
	v_mul_f32_e32 v98, v98, v102
	v_mul_f32_e32 v99, v99, v103
	v_mul_f32_e32 v100, v100, v104
	v_mul_f32_e32 v101, v101, v105
	v_cvt_pk_bf16_f32 v110, v106, v107
	v_cvt_pk_bf16_f32 v111, v108, v109
	v_cvt_pk_bf16_f32 v112, v98, v99
	v_cvt_pk_bf16_f32 v113, v100, v101
	s_nop 0
	global_store_dwordx4 v[160:161], v[110:113], off sc1
	v_lshl_add_u64 v[160:161], s[100:101], 0, v[160:161]
	v_mul_f32_e32 v88, v88, v154
	v_mul_f32_e32 v92, v92, v154
	v_mul_f32_e32 v89, v89, v154
	v_mul_f32_e32 v93, v93, v154
	v_mul_f32_e32 v90, v90, v154
	v_mul_f32_e32 v94, v94, v154
	v_mul_f32_e32 v91, v91, v154
	v_mul_f32_e32 v95, v95, v154
	v_mul_f32_e32 v80, v80, v154
	v_mul_f32_e32 v84, v84, v154
	v_mul_f32_e32 v81, v81, v154
	v_mul_f32_e32 v85, v85, v154
	v_mul_f32_e32 v82, v82, v154
	v_mul_f32_e32 v86, v86, v154
	v_mul_f32_e32 v83, v83, v154
	v_mul_f32_e32 v87, v87, v154
	v_mul_f32_e32 v166, 0xbfb8aa3b, v92
	v_mul_f32_e32 v167, 0xbfb8aa3b, v93
	v_mul_f32_e32 v168, 0xbfb8aa3b, v94
	v_mul_f32_e32 v169, 0xbfb8aa3b, v95
	v_mul_f32_e32 v170, 0xbfb8aa3b, v84
	v_mul_f32_e32 v171, 0xbfb8aa3b, v85
	v_mul_f32_e32 v172, 0xbfb8aa3b, v86
	v_mul_f32_e32 v173, 0xbfb8aa3b, v87
	v_exp_f32_e32 v166, v166
	v_exp_f32_e32 v167, v167
	v_exp_f32_e32 v168, v168
	v_exp_f32_e32 v169, v169
	v_exp_f32_e32 v170, v170
	v_exp_f32_e32 v171, v171
	v_exp_f32_e32 v172, v172
	v_exp_f32_e32 v173, v173
	v_add_f32_e32 v166, 1.0, v166
	v_add_f32_e32 v167, 1.0, v167
	v_add_f32_e32 v168, 1.0, v168
	v_add_f32_e32 v169, 1.0, v169
	v_add_f32_e32 v170, 1.0, v170
	v_add_f32_e32 v171, 1.0, v171
	v_add_f32_e32 v172, 1.0, v172
	v_add_f32_e32 v173, 1.0, v173
	v_rcp_f32_e32 v166, v166
	v_rcp_f32_e32 v167, v167
	v_rcp_f32_e32 v168, v168
	v_rcp_f32_e32 v169, v169
	v_rcp_f32_e32 v170, v170
	v_rcp_f32_e32 v171, v171
	v_rcp_f32_e32 v172, v172
	v_rcp_f32_e32 v173, v173
	v_mul_f32_e32 v92, v92, v166
	v_mul_f32_e32 v93, v93, v167
	v_mul_f32_e32 v94, v94, v168
	v_mul_f32_e32 v95, v95, v169
	v_mul_f32_e32 v84, v84, v170
	v_mul_f32_e32 v85, v85, v171
	v_mul_f32_e32 v86, v86, v172
	v_mul_f32_e32 v87, v87, v173
	v_mul_f32_e32 v88, v88, v92
	v_mul_f32_e32 v89, v89, v93
	v_mul_f32_e32 v90, v90, v94
	v_mul_f32_e32 v91, v91, v95
	v_mul_f32_e32 v80, v80, v84
	v_mul_f32_e32 v81, v81, v85
	v_mul_f32_e32 v82, v82, v86
	v_mul_f32_e32 v83, v83, v87
	v_cvt_pk_bf16_f32 v92, v88, v89
	v_cvt_pk_bf16_f32 v93, v90, v91
	v_cvt_pk_bf16_f32 v94, v80, v81
	v_cvt_pk_bf16_f32 v95, v82, v83
	s_nop 0
	global_store_dwordx4 v[160:161], v[92:95], off sc1
	v_lshl_add_u64 v[160:161], s[100:101], 0, v[160:161]
	v_mul_f32_e32 v72, v72, v155
	v_mul_f32_e32 v76, v76, v155
	v_mul_f32_e32 v73, v73, v155
	v_mul_f32_e32 v77, v77, v155
	v_mul_f32_e32 v74, v74, v155
	v_mul_f32_e32 v78, v78, v155
	v_mul_f32_e32 v75, v75, v155
	v_mul_f32_e32 v79, v79, v155
	v_mul_f32_e32 v64, v64, v155
	v_mul_f32_e32 v68, v68, v155
	v_mul_f32_e32 v65, v65, v155
	v_mul_f32_e32 v69, v69, v155
	v_mul_f32_e32 v66, v66, v155
	v_mul_f32_e32 v70, v70, v155
	v_mul_f32_e32 v67, v67, v155
	v_mul_f32_e32 v71, v71, v155
	v_mul_f32_e32 v166, 0xbfb8aa3b, v76
	v_mul_f32_e32 v167, 0xbfb8aa3b, v77
	v_mul_f32_e32 v168, 0xbfb8aa3b, v78
	v_mul_f32_e32 v169, 0xbfb8aa3b, v79
	v_mul_f32_e32 v170, 0xbfb8aa3b, v68
	v_mul_f32_e32 v171, 0xbfb8aa3b, v69
	v_mul_f32_e32 v172, 0xbfb8aa3b, v70
	v_mul_f32_e32 v173, 0xbfb8aa3b, v71
	v_exp_f32_e32 v166, v166
	v_exp_f32_e32 v167, v167
	v_exp_f32_e32 v168, v168
	v_exp_f32_e32 v169, v169
	v_exp_f32_e32 v170, v170
	v_exp_f32_e32 v171, v171
	v_exp_f32_e32 v172, v172
	v_exp_f32_e32 v173, v173
	v_add_f32_e32 v166, 1.0, v166
	v_add_f32_e32 v167, 1.0, v167
	v_add_f32_e32 v168, 1.0, v168
	v_add_f32_e32 v169, 1.0, v169
	v_add_f32_e32 v170, 1.0, v170
	v_add_f32_e32 v171, 1.0, v171
	v_add_f32_e32 v172, 1.0, v172
	v_add_f32_e32 v173, 1.0, v173
	v_rcp_f32_e32 v166, v166
	v_rcp_f32_e32 v167, v167
	v_rcp_f32_e32 v168, v168
	v_rcp_f32_e32 v169, v169
	v_rcp_f32_e32 v170, v170
	v_rcp_f32_e32 v171, v171
	v_rcp_f32_e32 v172, v172
	v_rcp_f32_e32 v173, v173
	v_mul_f32_e32 v76, v76, v166
	v_mul_f32_e32 v77, v77, v167
	v_mul_f32_e32 v78, v78, v168
	v_mul_f32_e32 v79, v79, v169
	v_mul_f32_e32 v68, v68, v170
	v_mul_f32_e32 v69, v69, v171
	v_mul_f32_e32 v70, v70, v172
	v_mul_f32_e32 v71, v71, v173
	v_mul_f32_e32 v72, v72, v76
	v_mul_f32_e32 v73, v73, v77
	v_mul_f32_e32 v74, v74, v78
	v_mul_f32_e32 v75, v75, v79
	v_mul_f32_e32 v64, v64, v68
	v_mul_f32_e32 v65, v65, v69
	v_mul_f32_e32 v66, v66, v70
	v_mul_f32_e32 v67, v67, v71
	v_cvt_pk_bf16_f32 v76, v72, v73
	v_cvt_pk_bf16_f32 v77, v74, v75
	v_cvt_pk_bf16_f32 v78, v64, v65
	v_cvt_pk_bf16_f32 v79, v66, v67
	s_nop 0
	global_store_dwordx4 v[160:161], v[76:79], off sc1
	v_lshl_add_u64 v[160:161], s[98:99], 0, v[160:161]
	v_mul_f32_e32 v56, v56, v156
	v_mul_f32_e32 v60, v60, v156
	v_mul_f32_e32 v57, v57, v156
	v_mul_f32_e32 v61, v61, v156
	v_mul_f32_e32 v58, v58, v156
	v_mul_f32_e32 v62, v62, v156
	v_mul_f32_e32 v59, v59, v156
	v_mul_f32_e32 v63, v63, v156
	v_mul_f32_e32 v48, v48, v156
	v_mul_f32_e32 v52, v52, v156
	v_mul_f32_e32 v49, v49, v156
	v_mul_f32_e32 v53, v53, v156
	v_mul_f32_e32 v50, v50, v156
	v_mul_f32_e32 v54, v54, v156
	v_mul_f32_e32 v51, v51, v156
	v_mul_f32_e32 v55, v55, v156
	v_mul_f32_e32 v166, 0xbfb8aa3b, v60
	v_mul_f32_e32 v167, 0xbfb8aa3b, v61
	v_mul_f32_e32 v168, 0xbfb8aa3b, v62
	v_mul_f32_e32 v169, 0xbfb8aa3b, v63
	v_mul_f32_e32 v170, 0xbfb8aa3b, v52
	v_mul_f32_e32 v171, 0xbfb8aa3b, v53
	v_mul_f32_e32 v172, 0xbfb8aa3b, v54
	v_mul_f32_e32 v173, 0xbfb8aa3b, v55
	v_exp_f32_e32 v166, v166
	v_exp_f32_e32 v167, v167
	v_exp_f32_e32 v168, v168
	v_exp_f32_e32 v169, v169
	v_exp_f32_e32 v170, v170
	v_exp_f32_e32 v171, v171
	v_exp_f32_e32 v172, v172
	v_exp_f32_e32 v173, v173
	v_add_f32_e32 v166, 1.0, v166
	v_add_f32_e32 v167, 1.0, v167
	v_add_f32_e32 v168, 1.0, v168
	v_add_f32_e32 v169, 1.0, v169
	v_add_f32_e32 v170, 1.0, v170
	v_add_f32_e32 v171, 1.0, v171
	v_add_f32_e32 v172, 1.0, v172
	v_add_f32_e32 v173, 1.0, v173
	v_rcp_f32_e32 v166, v166
	v_rcp_f32_e32 v167, v167
	v_rcp_f32_e32 v168, v168
	v_rcp_f32_e32 v169, v169
	v_rcp_f32_e32 v170, v170
	v_rcp_f32_e32 v171, v171
	v_rcp_f32_e32 v172, v172
	v_rcp_f32_e32 v173, v173
	v_mul_f32_e32 v60, v60, v166
	v_mul_f32_e32 v61, v61, v167
	v_mul_f32_e32 v62, v62, v168
	v_mul_f32_e32 v63, v63, v169
	v_mul_f32_e32 v52, v52, v170
	v_mul_f32_e32 v53, v53, v171
	v_mul_f32_e32 v54, v54, v172
	v_mul_f32_e32 v55, v55, v173
	v_mul_f32_e32 v56, v56, v60
	v_mul_f32_e32 v57, v57, v61
	v_mul_f32_e32 v58, v58, v62
	v_mul_f32_e32 v59, v59, v63
	v_mul_f32_e32 v48, v48, v52
	v_mul_f32_e32 v49, v49, v53
	v_mul_f32_e32 v50, v50, v54
	v_mul_f32_e32 v51, v51, v55
	v_cvt_pk_bf16_f32 v60, v56, v57
	v_cvt_pk_bf16_f32 v61, v58, v59
	v_cvt_pk_bf16_f32 v62, v48, v49
	v_cvt_pk_bf16_f32 v63, v50, v51
	s_nop 0
	global_store_dwordx4 v[160:161], v[60:63], off sc1
	v_lshl_add_u64 v[160:161], s[100:101], 0, v[160:161]
	v_mul_f32_e32 v40, v40, v157
	v_mul_f32_e32 v44, v44, v157
	v_mul_f32_e32 v41, v41, v157
	v_mul_f32_e32 v45, v45, v157
	v_mul_f32_e32 v42, v42, v157
	v_mul_f32_e32 v46, v46, v157
	v_mul_f32_e32 v43, v43, v157
	v_mul_f32_e32 v47, v47, v157
	v_mul_f32_e32 v32, v32, v157
	v_mul_f32_e32 v36, v36, v157
	v_mul_f32_e32 v33, v33, v157
	v_mul_f32_e32 v37, v37, v157
	v_mul_f32_e32 v34, v34, v157
	v_mul_f32_e32 v38, v38, v157
	v_mul_f32_e32 v35, v35, v157
	v_mul_f32_e32 v39, v39, v157
	v_mul_f32_e32 v166, 0xbfb8aa3b, v44
	v_mul_f32_e32 v167, 0xbfb8aa3b, v45
	v_mul_f32_e32 v168, 0xbfb8aa3b, v46
	v_mul_f32_e32 v169, 0xbfb8aa3b, v47
	v_mul_f32_e32 v170, 0xbfb8aa3b, v36
	v_mul_f32_e32 v171, 0xbfb8aa3b, v37
	v_mul_f32_e32 v172, 0xbfb8aa3b, v38
	v_mul_f32_e32 v173, 0xbfb8aa3b, v39
	v_exp_f32_e32 v166, v166
	v_exp_f32_e32 v167, v167
	v_exp_f32_e32 v168, v168
	v_exp_f32_e32 v169, v169
	v_exp_f32_e32 v170, v170
	v_exp_f32_e32 v171, v171
	v_exp_f32_e32 v172, v172
	v_exp_f32_e32 v173, v173
	v_add_f32_e32 v166, 1.0, v166
	v_add_f32_e32 v167, 1.0, v167
	v_add_f32_e32 v168, 1.0, v168
	v_add_f32_e32 v169, 1.0, v169
	v_add_f32_e32 v170, 1.0, v170
	v_add_f32_e32 v171, 1.0, v171
	v_add_f32_e32 v172, 1.0, v172
	v_add_f32_e32 v173, 1.0, v173
	v_rcp_f32_e32 v166, v166
	v_rcp_f32_e32 v167, v167
	v_rcp_f32_e32 v168, v168
	v_rcp_f32_e32 v169, v169
	v_rcp_f32_e32 v170, v170
	v_rcp_f32_e32 v171, v171
	v_rcp_f32_e32 v172, v172
	v_rcp_f32_e32 v173, v173
	v_mul_f32_e32 v44, v44, v166
	v_mul_f32_e32 v45, v45, v167
	v_mul_f32_e32 v46, v46, v168
	v_mul_f32_e32 v47, v47, v169
	v_mul_f32_e32 v36, v36, v170
	v_mul_f32_e32 v37, v37, v171
	v_mul_f32_e32 v38, v38, v172
	v_mul_f32_e32 v39, v39, v173
	v_mul_f32_e32 v40, v40, v44
	v_mul_f32_e32 v41, v41, v45
	v_mul_f32_e32 v42, v42, v46
	v_mul_f32_e32 v43, v43, v47
	v_mul_f32_e32 v32, v32, v36
	v_mul_f32_e32 v33, v33, v37
	v_mul_f32_e32 v34, v34, v38
	v_mul_f32_e32 v35, v35, v39
	v_cvt_pk_bf16_f32 v44, v40, v41
	v_cvt_pk_bf16_f32 v45, v42, v43
	v_cvt_pk_bf16_f32 v46, v32, v33
	v_cvt_pk_bf16_f32 v47, v34, v35
	s_nop 0
	global_store_dwordx4 v[160:161], v[44:47], off sc1
	v_lshl_add_u64 v[160:161], s[100:101], 0, v[160:161]
	v_mul_f32_e32 v24, v24, v158
	v_mul_f32_e32 v28, v28, v158
	v_mul_f32_e32 v25, v25, v158
	v_mul_f32_e32 v29, v29, v158
	v_mul_f32_e32 v26, v26, v158
	v_mul_f32_e32 v30, v30, v158
	v_mul_f32_e32 v27, v27, v158
	v_mul_f32_e32 v31, v31, v158
	v_mul_f32_e32 v16, v16, v158
	v_mul_f32_e32 v20, v20, v158
	v_mul_f32_e32 v17, v17, v158
	v_mul_f32_e32 v21, v21, v158
	v_mul_f32_e32 v18, v18, v158
	v_mul_f32_e32 v22, v22, v158
	v_mul_f32_e32 v19, v19, v158
	v_mul_f32_e32 v23, v23, v158
	v_mul_f32_e32 v166, 0xbfb8aa3b, v28
	v_mul_f32_e32 v167, 0xbfb8aa3b, v29
	v_mul_f32_e32 v168, 0xbfb8aa3b, v30
	v_mul_f32_e32 v169, 0xbfb8aa3b, v31
	v_mul_f32_e32 v170, 0xbfb8aa3b, v20
	v_mul_f32_e32 v171, 0xbfb8aa3b, v21
	v_mul_f32_e32 v172, 0xbfb8aa3b, v22
	v_mul_f32_e32 v173, 0xbfb8aa3b, v23
	v_exp_f32_e32 v166, v166
	v_exp_f32_e32 v167, v167
	v_exp_f32_e32 v168, v168
	v_exp_f32_e32 v169, v169
	v_exp_f32_e32 v170, v170
	v_exp_f32_e32 v171, v171
	v_exp_f32_e32 v172, v172
	v_exp_f32_e32 v173, v173
	v_add_f32_e32 v166, 1.0, v166
	v_add_f32_e32 v167, 1.0, v167
	v_add_f32_e32 v168, 1.0, v168
	v_add_f32_e32 v169, 1.0, v169
	v_add_f32_e32 v170, 1.0, v170
	v_add_f32_e32 v171, 1.0, v171
	v_add_f32_e32 v172, 1.0, v172
	v_add_f32_e32 v173, 1.0, v173
	v_rcp_f32_e32 v166, v166
	v_rcp_f32_e32 v167, v167
	v_rcp_f32_e32 v168, v168
	v_rcp_f32_e32 v169, v169
	v_rcp_f32_e32 v170, v170
	v_rcp_f32_e32 v171, v171
	v_rcp_f32_e32 v172, v172
	v_rcp_f32_e32 v173, v173
	v_mul_f32_e32 v28, v28, v166
	v_mul_f32_e32 v29, v29, v167
	v_mul_f32_e32 v30, v30, v168
	v_mul_f32_e32 v31, v31, v169
	v_mul_f32_e32 v20, v20, v170
	v_mul_f32_e32 v21, v21, v171
	v_mul_f32_e32 v22, v22, v172
	v_mul_f32_e32 v23, v23, v173
	v_mul_f32_e32 v24, v24, v28
	v_mul_f32_e32 v25, v25, v29
	v_mul_f32_e32 v26, v26, v30
	v_mul_f32_e32 v27, v27, v31
	v_mul_f32_e32 v16, v16, v20
	v_mul_f32_e32 v17, v17, v21
	v_mul_f32_e32 v18, v18, v22
	v_mul_f32_e32 v19, v19, v23
	v_cvt_pk_bf16_f32 v28, v24, v25
	v_cvt_pk_bf16_f32 v29, v26, v27
	v_cvt_pk_bf16_f32 v30, v16, v17
	v_cvt_pk_bf16_f32 v31, v18, v19
	s_nop 0
	global_store_dwordx4 v[160:161], v[28:31], off sc1
	v_lshl_add_u64 v[160:161], s[100:101], 0, v[160:161]
	v_mul_f32_e32 v8, v8, v159
	v_mul_f32_e32 v12, v12, v159
	v_mul_f32_e32 v9, v9, v159
	v_mul_f32_e32 v13, v13, v159
	v_mul_f32_e32 v10, v10, v159
	v_mul_f32_e32 v14, v14, v159
	v_mul_f32_e32 v11, v11, v159
	v_mul_f32_e32 v15, v15, v159
	v_mul_f32_e32 v0, v0, v159
	v_mul_f32_e32 v4, v4, v159
	v_mul_f32_e32 v1, v1, v159
	v_mul_f32_e32 v5, v5, v159
	v_mul_f32_e32 v2, v2, v159
	v_mul_f32_e32 v6, v6, v159
	v_mul_f32_e32 v3, v3, v159
	v_mul_f32_e32 v7, v7, v159
	v_mul_f32_e32 v166, 0xbfb8aa3b, v12
	v_mul_f32_e32 v167, 0xbfb8aa3b, v13
	v_mul_f32_e32 v168, 0xbfb8aa3b, v14
	v_mul_f32_e32 v169, 0xbfb8aa3b, v15
	v_mul_f32_e32 v170, 0xbfb8aa3b, v4
	v_mul_f32_e32 v171, 0xbfb8aa3b, v5
	v_mul_f32_e32 v172, 0xbfb8aa3b, v6
	v_mul_f32_e32 v173, 0xbfb8aa3b, v7
	v_exp_f32_e32 v166, v166
	v_exp_f32_e32 v167, v167
	v_exp_f32_e32 v168, v168
	v_exp_f32_e32 v169, v169
	v_exp_f32_e32 v170, v170
	v_exp_f32_e32 v171, v171
	v_exp_f32_e32 v172, v172
	v_exp_f32_e32 v173, v173
	v_add_f32_e32 v166, 1.0, v166
	v_add_f32_e32 v167, 1.0, v167
	v_add_f32_e32 v168, 1.0, v168
	v_add_f32_e32 v169, 1.0, v169
	v_add_f32_e32 v170, 1.0, v170
	v_add_f32_e32 v171, 1.0, v171
	v_add_f32_e32 v172, 1.0, v172
	v_add_f32_e32 v173, 1.0, v173
	v_rcp_f32_e32 v166, v166
	v_rcp_f32_e32 v167, v167
	v_rcp_f32_e32 v168, v168
	v_rcp_f32_e32 v169, v169
	v_rcp_f32_e32 v170, v170
	v_rcp_f32_e32 v171, v171
	v_rcp_f32_e32 v172, v172
	v_rcp_f32_e32 v173, v173
	v_mul_f32_e32 v12, v12, v166
	v_mul_f32_e32 v13, v13, v167
	v_mul_f32_e32 v14, v14, v168
	v_mul_f32_e32 v15, v15, v169
	v_mul_f32_e32 v4, v4, v170
	v_mul_f32_e32 v5, v5, v171
	v_mul_f32_e32 v6, v6, v172
	v_mul_f32_e32 v7, v7, v173
	v_mul_f32_e32 v8, v8, v12
	v_mul_f32_e32 v9, v9, v13
	v_mul_f32_e32 v10, v10, v14
	v_mul_f32_e32 v11, v11, v15
	v_mul_f32_e32 v0, v0, v4
	v_mul_f32_e32 v1, v1, v5
	v_mul_f32_e32 v2, v2, v6
	v_mul_f32_e32 v3, v3, v7
	v_cvt_pk_bf16_f32 v12, v8, v9
	v_cvt_pk_bf16_f32 v13, v10, v11
	v_cvt_pk_bf16_f32 v14, v0, v1
	v_cvt_pk_bf16_f32 v15, v2, v3
	s_nop 0
	global_store_dwordx4 v[160:161], v[12:15], off sc1
	s_nop 1
	s_mov_b64 s[22:23], -1
	s_cbranch_vccnz .LBB0_142
	s_branch .LBB0_141
.LBB0_154:
	s_waitcnt vmcnt(0)
	s_mov_b32 s40, 0x26000
	s_mov_b32 s41, 0x2c000
	s_and_b64 vcc, exec, s[10:11]
	s_cbranch_vccz .Lgu_noextra
	s_barrier
.Lgu_noextra:

	s_barrier
